# adds ssd pass-3 row prefetch and skips MFMAs of the padding-only wave columns in the last in-proj N tile
# baseline (speedup 1.0000x reference)
; #define LDSAS __attribute__((address_space(3)))
; #define G_ISSUE(kt, st) do { G_ISSUE1(kt, st, 0); G_ISSUE1(kt, st, 1); G_ISSUE1(kt, st, 2); G_ISSUE1(kt, st, 3); } while (0)
; template <bool LOWREG = false>
; __device__ __forceinline__ void gemm_core(const bf16_t* __restrict__ A, int lda, const bf16_t* __restrict__ Bt, int ldb, int K, f32x4 (&acc)[8][4], unsigned char* smem, int tid) {
;     ...
;     const int lane = tid & 63, w = __builtin_amdgcn_readfirstlane(tid >> 6), wm = w >> 2, wn = w & 3, idx = lane & 15, kq = lane >> 4;
;     unsigned offA[4], offB[4];
; #pragma unroll
;     for (int j = 0; j < 4; ++j) { const int row = (j * 8 + w) * 8 + (lane >> 3), c = (lane & 7) ^ ((row >> 1) & 7);
;         offA[j] = (unsigned)(row * lda + c * 8) * 2u; offB[j] = (unsigned)(row * ldb + c * 8) * 2u; }
; #pragma unroll
;     for (int mi = 0; mi < 8; ++mi)
; #pragma unroll
;         for (int ni = 0; ni < 4; ++ni) acc[mi][ni] = (f32x4){0.f, 0.f, 0.f, 0.f};
;     LDSAS unsigned char* lds = (LDSAS unsigned char*)smem;
;     ...
;     const int nk = K >> 6;
;     G_ISSUE(0, 0);
;     asm volatile("s_waitcnt vmcnt(0)" ::: "memory");
;     __syncthreads();
;     const int swz = (idx >> 1) & 7;
;     const int aoff = (wm * 128 + idx) * 128, boff = G_AB + (wn * 64 + idx) * 128;
; __device__ void gemm1_phase(const Params& p, int l, int hb, unsigned char* smem) {
;     ...
;     for (int t = blockIdx.x; t < NTILES; t += gridDim.x) {
;         const int grp = t / GRP, r = t % GRP, jx = NT * (r & 7) + (r >> 3), mt = grp * 8 + (jx & 7), nt = jx >> 3;
;         const int m0 = mt * 256, n0 = nt * 256;
;         f32x4 acc[8][4];
;         int tid = threadIdx.x;
;         gemm_core(H + (size_t)m0 * 1024, 1024, Wt + (size_t)n0 * 1024, 1024, 1024, acc, smem, tid);
.LBB0_254:
	s_mul_hi_i32 s9, s60, 0x78787879
	s_lshr_b32 s11, s9, 31
	s_ashr_i32 s9, s9, 7
	s_add_i32 s9, s9, s11
	s_mul_i32 s11, s9, 0x110
	s_sub_i32 s11, s60, s11
	s_and_b32 s12, s11, 7
	s_mul_i32 s12, s12, 34
	s_ashr_i32 s11, s11, 3
	s_add_i32 s12, s12, s11
	s_lshl_b32 s11, s12, 8
	s_lshl_b32 s9, s9, 11
	s_and_b32 s11, s11, 0x700
	s_or_b32 s56, s11, s9
	s_lshl_b32 s11, s12, 5
	s_ashr_i32 s57, s56, 31
	s_and_b32 s36, s11, 0xffffff00
	s_lshl_b64 s[16:17], s[56:57], 11
	s_add_u32 s18, s92, s16
	s_addc_u32 s19, s93, s17
	s_ashr_i32 s37, s36, 31
	s_lshl_b64 s[20:21], s[36:37], 11
	v_mov_b32_e32 v0, v210
	s_add_u32 s22, s94, s20
	s_addc_u32 s23, s95, s21
	v_readfirstlane_b32 s12, v0
	s_ashr_i32 s24, s12, 6
	s_and_b32 s101, s24, 3
	s_cmp_lg_u32 s101, 0
	s_cselect_b32 s101, 1, 0
	s_cmp_eq_u32 s36, 0x2100
	s_cselect_b32 s101, s101, 0
	v_bfe_u32 v2, v0, 3, 3
	v_lshl_or_b32 v3, s24, 3, v2
	v_lshrrev_b32_e32 v4, 1, v3
	v_xor_b32_e32 v4, v4, v0
	v_lshlrev_b32_e32 v4, 4, v4
	s_lshl_b32 s9, s24, 10
	v_and_b32_e32 v4, 0x70, v4
	s_add_i32 s9, s9, 0
	v_lshl_or_b32 v3, v3, 11, v4
	s_mov_b32 m0, s9
	v_add_u32_e32 v5, 0x20000, v3
	global_load_lds_dwordx4 v3, s[18:19]
	s_add_i32 m0, s9, 0x8000
	v_add_u32_e32 v6, 0x40000, v3
	global_load_lds_dwordx4 v3, s[22:23]
	s_add_i32 m0, s9, 0x2000
	v_add_u32_e32 v7, 0x60000, v3
	global_load_lds_dwordx4 v5, s[18:19]
	s_add_i32 m0, s9, 0xa000
	v_and_b32_e32 v1, 15, v0
	global_load_lds_dwordx4 v5, s[22:23]
	s_add_i32 m0, s9, 0x4000
	v_bfe_u32 v8, v0, 4, 2
	global_load_lds_dwordx4 v6, s[18:19]
	s_add_i32 m0, s9, 0xc000
	v_lshrrev_b32_e32 v3, 1, v0
	global_load_lds_dwordx4 v6, s[22:23]
	s_add_i32 m0, s9, 0x6000
	v_bfe_u32 v0, v0, 1, 3
	global_load_lds_dwordx4 v7, s[18:19]
	s_add_i32 m0, s9, 0xe000
	s_lshr_b32 s18, s12, 1
	global_load_lds_dwordx4 v7, s[22:23]
	s_and_b32 s18, s18, 0x1ffff80
	s_and_b32 s12, s12, 0xc0
	v_or_b32_e32 v5, s18, v1
	v_or_b32_e32 v1, s12, v1
	s_lshl_b32 s12, s24, 14
	s_add_u32 s16, s96, s16
	v_lshlrev_b32_e32 v149, 7, v5
	v_bitop3_b32 v0, v8, v0, 4 bitop3:0x36
	v_lshlrev_b32_e32 v5, 11, v2
	s_addc_u32 s17, s97, s17
	s_add_i32 s18, s12, 0x20000
	v_lshlrev_b32_e32 v147, 7, v1
	v_bitop3_b32 v1, v8, v3, 7 bitop3:0x78
	v_lshlrev_b32_e32 v146, 4, v0
	v_or3_b32 v80, s12, v5, v4
	v_or3_b32 v0, s18, v5, v4
	s_add_i32 s18, s12, 0x40000
	s_add_i32 s12, s12, 0x60000
	v_lshlrev_b32_e32 v148, 4, v1
	v_mov_b32_e32 v1, v81
	v_or3_b32 v2, s18, v5, v4
	v_mov_b32_e32 v3, v81
	v_or3_b32 v4, s12, v5, v4
	v_mov_b32_e32 v5, v81
	v_lshl_add_u64 v[130:131], s[16:17], 0, v[80:81]
	v_lshl_add_u64 v[132:133], s[16:17], 0, v[0:1]
	v_lshl_add_u64 v[134:135], s[16:17], 0, v[2:3]
	v_lshl_add_u64 v[136:137], s[16:17], 0, v[4:5]
	s_add_u32 s16, s64, s20
	s_waitcnt vmcnt(0)
	s_addc_u32 s17, s65, s21
	v_lshl_add_u64 v[140:141], s[16:17], 0, v[0:1]
	v_mov_b32_e32 v0, 0
	v_lshl_add_u64 v[138:139], s[16:17], 0, v[80:81]
	v_lshl_add_u64 v[142:143], s[16:17], 0, v[2:3]
	v_lshl_add_u64 v[144:145], s[16:17], 0, v[4:5]
	s_mov_b32 s12, 0
	s_mov_b64 s[38:39], 0
	v_mov_b32_e32 v1, v0
	v_mov_b32_e32 v2, v0
	v_mov_b32_e32 v3, v0
	v_mov_b32_e32 v4, v0
	v_mov_b32_e32 v5, v0
	v_mov_b32_e32 v6, v0
	v_mov_b32_e32 v7, v0
	v_mov_b32_e32 v8, v0
	v_mov_b32_e32 v9, v0
	s_waitcnt vmcnt(0)
	v_mov_b32_e32 v10, v0
	v_mov_b32_e32 v11, v0
	v_mov_b32_e32 v12, v0
	v_mov_b32_e32 v13, v0
	v_mov_b32_e32 v14, v0
	v_mov_b32_e32 v15, v0
	v_mov_b32_e32 v16, v0
	v_mov_b32_e32 v17, v0
	v_mov_b32_e32 v18, v0
	v_mov_b32_e32 v19, v0
	v_mov_b32_e32 v20, v0
	v_mov_b32_e32 v21, v0
	v_mov_b32_e32 v22, v0
	v_mov_b32_e32 v23, v0
	v_mov_b32_e32 v24, v0
	v_mov_b32_e32 v25, v0
	v_mov_b32_e32 v26, v0
	v_mov_b32_e32 v27, v0
	v_mov_b32_e32 v28, v0
	v_mov_b32_e32 v29, v0
	v_mov_b32_e32 v30, v0
	v_mov_b32_e32 v31, v0
	v_mov_b32_e32 v32, v0
	v_mov_b32_e32 v33, v0
	v_mov_b32_e32 v34, v0
	v_mov_b32_e32 v35, v0
	v_mov_b32_e32 v36, v0
	v_mov_b32_e32 v37, v0
	v_mov_b32_e32 v38, v0
	v_mov_b32_e32 v39, v0
	v_mov_b32_e32 v40, v0
	v_mov_b32_e32 v41, v0
	v_mov_b32_e32 v42, v0
	v_mov_b32_e32 v43, v0
	v_mov_b32_e32 v44, v0
	v_mov_b32_e32 v45, v0
	v_mov_b32_e32 v46, v0
	v_mov_b32_e32 v47, v0
	v_mov_b32_e32 v48, v0
	v_mov_b32_e32 v49, v0
	v_mov_b32_e32 v50, v0
	v_mov_b32_e32 v51, v0
	v_mov_b32_e32 v52, v0
	v_mov_b32_e32 v53, v0
	v_mov_b32_e32 v54, v0
	v_mov_b32_e32 v55, v0
	v_mov_b32_e32 v56, v0
	v_mov_b32_e32 v57, v0
	v_mov_b32_e32 v58, v0
	v_mov_b32_e32 v59, v0
	v_mov_b32_e32 v60, v0
	v_mov_b32_e32 v61, v0
	v_mov_b32_e32 v62, v0
	v_mov_b32_e32 v63, v0
	v_mov_b32_e32 v64, v0
	v_mov_b32_e32 v65, v0
	v_mov_b32_e32 v66, v0
	v_mov_b32_e32 v67, v0
	v_mov_b32_e32 v68, v0
	v_mov_b32_e32 v69, v0
	v_mov_b32_e32 v70, v0
	v_mov_b32_e32 v71, v0
	v_mov_b32_e32 v72, v0
	v_mov_b32_e32 v73, v0
	v_mov_b32_e32 v74, v0
	v_mov_b32_e32 v75, v0
	v_mov_b32_e32 v76, v0
	v_mov_b32_e32 v77, v0
	v_mov_b32_e32 v78, v0
	v_mov_b32_e32 v79, v0
	v_mov_b32_e32 v82, v0
	v_mov_b32_e32 v83, v0
	v_mov_b32_e32 v84, v0
	v_mov_b32_e32 v85, v0
	v_mov_b32_e32 v86, v0
	v_mov_b32_e32 v87, v0
	v_mov_b32_e32 v88, v0
	v_mov_b32_e32 v89, v0
	v_mov_b32_e32 v90, v0
	v_mov_b32_e32 v91, v0
	v_mov_b32_e32 v92, v0
	v_mov_b32_e32 v93, v0
	v_mov_b32_e32 v94, v0
	v_mov_b32_e32 v95, v0
	v_mov_b32_e32 v96, v0
	v_mov_b32_e32 v97, v0
	v_mov_b32_e32 v98, v0
	v_mov_b32_e32 v99, v0
	v_mov_b32_e32 v100, v0
	v_mov_b32_e32 v101, v0
	v_mov_b32_e32 v102, v0
	v_mov_b32_e32 v103, v0
	v_mov_b32_e32 v104, v0
	v_mov_b32_e32 v105, v0
	v_mov_b32_e32 v106, v0
	v_mov_b32_e32 v107, v0
	v_mov_b32_e32 v108, v0
	v_mov_b32_e32 v109, v0
	v_mov_b32_e32 v110, v0
	v_mov_b32_e32 v111, v0
	v_mov_b32_e32 v112, v0
	v_mov_b32_e32 v113, v0
	v_mov_b32_e32 v114, v0
	v_mov_b32_e32 v115, v0
	v_mov_b32_e32 v116, v0
	v_mov_b32_e32 v117, v0
	v_mov_b32_e32 v118, v0
	v_mov_b32_e32 v119, v0
	v_mov_b32_e32 v120, v0
	v_mov_b32_e32 v121, v0
	v_mov_b32_e32 v122, v0
	v_mov_b32_e32 v123, v0
	v_mov_b32_e32 v124, v0
	v_mov_b32_e32 v125, v0
	v_mov_b32_e32 v126, v0
	v_mov_b32_e32 v127, v0
	v_mov_b32_e32 v128, v0
	v_mov_b32_e32 v129, v0
	s_waitcnt lgkmcnt(0)
	s_barrier
; template <bool LOWREG = false>
; __device__ __forceinline__ void gemm_core(const bf16_t* __restrict__ A, int lda, const bf16_t* __restrict__ Bt, int ldb, int K, f32x4 (&acc)[8][4], unsigned char* smem, int tid) {
;     ...
;     for (int kt = 0; kt < nk; ++kt) {
;         const int st = kt & 1;
;         const bool more = kt + 1 < nk;
;         const unsigned char* sb = smem + st * G_STAGE;
;         if constexpr (!LOWREG) {
; #pragma unroll
;         for (int ks = 0; ks < 2; ++ks) {
;             bf16x8 bfr[4], af[8];
;             const int co = ((ks * 4 + kq) ^ swz) * 16;
; #pragma unroll
;             for (int ni = 0; ni < 4; ++ni) bfr[ni] = *(const bf16x8*)(sb + boff + ni * 2048 + co);
; #pragma unroll
;             for (int mi = 0; mi < 8; ++mi) af[mi] = *(const bf16x8*)(sb + aoff + mi * 2048 + co);
;             if (more) { G_ISSUE1(kt + 1, st ^ 1, ks * 2); G_ISSUE1(kt + 1, st ^ 1, ks * 2 + 1); }
;             __builtin_amdgcn_sched_barrier(0);
;             __builtin_amdgcn_s_setprio(1);
; #pragma unroll
;             for (int mi = 0; mi < 8; ++mi)
; #pragma unroll
;                 for (int ni = 0; ni < 4; ++ni) acc[mi][ni] = __builtin_amdgcn_mfma_f32_16x16x32_bf16(bfr[ni], af[mi], acc[mi][ni], 0, 0, 0);
;             __builtin_amdgcn_s_setprio(0);
;             __builtin_amdgcn_sched_barrier(0);
;         }
.LBB0_255:
	s_and_b32 s16, s12, 0x10000
	s_add_i32 s17, s16, 0
	s_xor_b32 s16, s16, 0x10000
	v_add_u32_e32 v80, s17, v147
	v_add_u32_e32 v179, s17, v149
	s_add_i32 s16, s9, s16
	v_add_u32_e32 v162, v80, v148
	v_add_u32_e32 v196, v179, v148
	v_lshl_add_u64 v[200:201], v[130:131], 0, s[38:39]
	s_mov_b32 m0, s16
	ds_read_b128 v[150:153], v162 offset:32768
	ds_read_b128 v[154:157], v162 offset:34816
	ds_read_b128 v[158:161], v162 offset:36864
	ds_read_b128 v[162:165], v162 offset:38912
	ds_read_b128 v[166:169], v196
	ds_read_b128 v[170:173], v196 offset:2048
	ds_read_b128 v[174:177], v196 offset:4096
	ds_read_b128 v[180:183], v196 offset:6144
	ds_read_b128 v[184:187], v196 offset:8192
	ds_read_b128 v[188:191], v196 offset:10240
	ds_read_b128 v[192:195], v196 offset:12288
	ds_read_b128 v[196:199], v196 offset:14336
	global_load_lds_dwordx4 v[200:201], off
	v_lshl_add_u64 v[200:201], v[138:139], 0, s[38:39]
	s_add_i32 m0, s16, 0x8000
	s_nop 0
	global_load_lds_dwordx4 v[200:201], off
	v_lshl_add_u64 v[200:201], v[132:133], 0, s[38:39]
	s_add_i32 m0, s16, 0x2000
	s_nop 0
	global_load_lds_dwordx4 v[200:201], off
	v_lshl_add_u64 v[200:201], v[140:141], 0, s[38:39]
	s_add_i32 m0, s16, 0xa000
	s_nop 0
	global_load_lds_dwordx4 v[200:201], off
	s_cmp_lg_u32 s101, 0
	s_cbranch_scc1 .Lg1_dtskip1
	s_setprio 1
	s_waitcnt lgkmcnt(0)
	v_mfma_f32_16x16x32_bf16 v[126:129], v[150:153], v[166:169], v[126:129]
	v_mfma_f32_16x16x32_bf16 v[122:125], v[154:157], v[166:169], v[122:125]
	v_mfma_f32_16x16x32_bf16 v[118:121], v[158:161], v[166:169], v[118:121]
	v_mfma_f32_16x16x32_bf16 v[114:117], v[162:165], v[166:169], v[114:117]
	v_mfma_f32_16x16x32_bf16 v[110:113], v[150:153], v[170:173], v[110:113]
	v_mfma_f32_16x16x32_bf16 v[106:109], v[154:157], v[170:173], v[106:109]
	v_mfma_f32_16x16x32_bf16 v[102:105], v[158:161], v[170:173], v[102:105]
	v_mfma_f32_16x16x32_bf16 v[98:101], v[162:165], v[170:173], v[98:101]
	v_mfma_f32_16x16x32_bf16 v[94:97], v[150:153], v[174:177], v[94:97]
	v_mfma_f32_16x16x32_bf16 v[90:93], v[154:157], v[174:177], v[90:93]
	v_mfma_f32_16x16x32_bf16 v[86:89], v[158:161], v[174:177], v[86:89]
	v_mfma_f32_16x16x32_bf16 v[82:85], v[162:165], v[174:177], v[82:85]
	v_mfma_f32_16x16x32_bf16 v[76:79], v[150:153], v[180:183], v[76:79]
	v_mfma_f32_16x16x32_bf16 v[72:75], v[154:157], v[180:183], v[72:75]
	v_mfma_f32_16x16x32_bf16 v[68:71], v[158:161], v[180:183], v[68:71]
	v_mfma_f32_16x16x32_bf16 v[64:67], v[162:165], v[180:183], v[64:67]
	v_mfma_f32_16x16x32_bf16 v[60:63], v[150:153], v[184:187], v[60:63]
	v_mfma_f32_16x16x32_bf16 v[56:59], v[154:157], v[184:187], v[56:59]
	v_mfma_f32_16x16x32_bf16 v[52:55], v[158:161], v[184:187], v[52:55]
	v_mfma_f32_16x16x32_bf16 v[48:51], v[162:165], v[184:187], v[48:51]
	v_mfma_f32_16x16x32_bf16 v[44:47], v[150:153], v[188:191], v[44:47]
	v_mfma_f32_16x16x32_bf16 v[40:43], v[154:157], v[188:191], v[40:43]
	v_mfma_f32_16x16x32_bf16 v[36:39], v[158:161], v[188:191], v[36:39]
	v_mfma_f32_16x16x32_bf16 v[32:35], v[162:165], v[188:191], v[32:35]
	v_mfma_f32_16x16x32_bf16 v[28:31], v[150:153], v[192:195], v[28:31]
	v_mfma_f32_16x16x32_bf16 v[24:27], v[154:157], v[192:195], v[24:27]
	v_mfma_f32_16x16x32_bf16 v[20:23], v[158:161], v[192:195], v[20:23]
	v_mfma_f32_16x16x32_bf16 v[16:19], v[162:165], v[192:195], v[16:19]
	v_mfma_f32_16x16x32_bf16 v[12:15], v[150:153], v[196:199], v[12:15]
	v_mfma_f32_16x16x32_bf16 v[8:11], v[154:157], v[196:199], v[8:11]
	v_mfma_f32_16x16x32_bf16 v[4:7], v[158:161], v[196:199], v[4:7]
	v_mfma_f32_16x16x32_bf16 v[0:3], v[162:165], v[196:199], v[0:3]
	s_setprio 0
.Lg1_dtskip1:
	s_waitcnt lgkmcnt(0)
	v_add_u32_e32 v80, v80, v146
	ds_read_b128 v[150:153], v80 offset:32768
	ds_read_b128 v[154:157], v80 offset:34816
	ds_read_b128 v[158:161], v80 offset:36864
	ds_read_b128 v[162:165], v80 offset:38912
	v_add_u32_e32 v80, v179, v146
	v_lshl_add_u64 v[200:201], v[134:135], 0, s[38:39]
	s_add_i32 m0, s16, 0x4000
	ds_read_b128 v[166:169], v80
	ds_read_b128 v[170:173], v80 offset:2048
	ds_read_b128 v[174:177], v80 offset:4096
	ds_read_b128 v[180:183], v80 offset:6144
	ds_read_b128 v[184:187], v80 offset:8192
	ds_read_b128 v[188:191], v80 offset:10240
	ds_read_b128 v[192:195], v80 offset:12288
	ds_read_b128 v[196:199], v80 offset:14336
	global_load_lds_dwordx4 v[200:201], off
	v_lshl_add_u64 v[200:201], v[142:143], 0, s[38:39]
	s_add_i32 m0, s16, 0xc000
	s_nop 0
	global_load_lds_dwordx4 v[200:201], off
	v_lshl_add_u64 v[200:201], v[136:137], 0, s[38:39]
	s_add_i32 m0, s16, 0x6000
	s_nop 0
	global_load_lds_dwordx4 v[200:201], off
	v_lshl_add_u64 v[200:201], v[144:145], 0, s[38:39]
	s_add_i32 m0, s16, 0xe000
	s_nop 0
	global_load_lds_dwordx4 v[200:201], off
	s_cmp_lg_u32 s101, 0
	s_cbranch_scc1 .Lg1_dtskip2
	s_setprio 1
	s_waitcnt lgkmcnt(0)
	v_mfma_f32_16x16x32_bf16 v[126:129], v[150:153], v[166:169], v[126:129]
	v_mfma_f32_16x16x32_bf16 v[122:125], v[154:157], v[166:169], v[122:125]
	v_mfma_f32_16x16x32_bf16 v[118:121], v[158:161], v[166:169], v[118:121]
	v_mfma_f32_16x16x32_bf16 v[114:117], v[162:165], v[166:169], v[114:117]
	v_mfma_f32_16x16x32_bf16 v[110:113], v[150:153], v[170:173], v[110:113]
	v_mfma_f32_16x16x32_bf16 v[106:109], v[154:157], v[170:173], v[106:109]
	v_mfma_f32_16x16x32_bf16 v[102:105], v[158:161], v[170:173], v[102:105]
	v_mfma_f32_16x16x32_bf16 v[98:101], v[162:165], v[170:173], v[98:101]
	v_mfma_f32_16x16x32_bf16 v[94:97], v[150:153], v[174:177], v[94:97]
	v_mfma_f32_16x16x32_bf16 v[90:93], v[154:157], v[174:177], v[90:93]
	v_mfma_f32_16x16x32_bf16 v[86:89], v[158:161], v[174:177], v[86:89]
	v_mfma_f32_16x16x32_bf16 v[82:85], v[162:165], v[174:177], v[82:85]
	v_mfma_f32_16x16x32_bf16 v[76:79], v[150:153], v[180:183], v[76:79]
	v_mfma_f32_16x16x32_bf16 v[72:75], v[154:157], v[180:183], v[72:75]
	v_mfma_f32_16x16x32_bf16 v[68:71], v[158:161], v[180:183], v[68:71]
	v_mfma_f32_16x16x32_bf16 v[64:67], v[162:165], v[180:183], v[64:67]
	v_mfma_f32_16x16x32_bf16 v[60:63], v[150:153], v[184:187], v[60:63]
	v_mfma_f32_16x16x32_bf16 v[56:59], v[154:157], v[184:187], v[56:59]
	v_mfma_f32_16x16x32_bf16 v[52:55], v[158:161], v[184:187], v[52:55]
	v_mfma_f32_16x16x32_bf16 v[48:51], v[162:165], v[184:187], v[48:51]
	v_mfma_f32_16x16x32_bf16 v[44:47], v[150:153], v[188:191], v[44:47]
	v_mfma_f32_16x16x32_bf16 v[40:43], v[154:157], v[188:191], v[40:43]
	v_mfma_f32_16x16x32_bf16 v[36:39], v[158:161], v[188:191], v[36:39]
	v_mfma_f32_16x16x32_bf16 v[32:35], v[162:165], v[188:191], v[32:35]
	v_mfma_f32_16x16x32_bf16 v[28:31], v[150:153], v[192:195], v[28:31]
	v_mfma_f32_16x16x32_bf16 v[24:27], v[154:157], v[192:195], v[24:27]
	v_mfma_f32_16x16x32_bf16 v[20:23], v[158:161], v[192:195], v[20:23]
	v_mfma_f32_16x16x32_bf16 v[16:19], v[162:165], v[192:195], v[16:19]
	v_mfma_f32_16x16x32_bf16 v[12:15], v[150:153], v[196:199], v[12:15]
	v_mfma_f32_16x16x32_bf16 v[8:11], v[154:157], v[196:199], v[8:11]
	v_mfma_f32_16x16x32_bf16 v[4:7], v[158:161], v[196:199], v[4:7]
	v_mfma_f32_16x16x32_bf16 v[0:3], v[162:165], v[196:199], v[0:3]
	s_setprio 0
; template <bool LOWREG = false>
; __device__ __forceinline__ void gemm_core(const bf16_t* __restrict__ A, int lda, const bf16_t* __restrict__ Bt, int ldb, int K, f32x4 (&acc)[8][4], unsigned char* smem, int tid) {
;     ...
;     for (int kt = 0; kt < nk; ++kt) {
;         const int st = kt & 1;
;         const bool more = kt + 1 < nk;
;         const unsigned char* sb = smem + st * G_STAGE;
;         if constexpr (!LOWREG) {
; #pragma unroll
;         for (int ks = 0; ks < 2; ++ks) {
;             bf16x8 bfr[4], af[8];
;             const int co = ((ks * 4 + kq) ^ swz) * 16;
; #pragma unroll
;             for (int ni = 0; ni < 4; ++ni) bfr[ni] = *(const bf16x8*)(sb + boff + ni * 2048 + co);
; #pragma unroll
;             for (int mi = 0; mi < 8; ++mi) af[mi] = *(const bf16x8*)(sb + aoff + mi * 2048 + co);
;             if (more) { G_ISSUE1(kt + 1, st ^ 1, ks * 2); G_ISSUE1(kt + 1, st ^ 1, ks * 2 + 1); }
;             __builtin_amdgcn_sched_barrier(0);
;             __builtin_amdgcn_s_setprio(1);
; #pragma unroll
;             for (int mi = 0; mi < 8; ++mi)
; #pragma unroll
;                 for (int ni = 0; ni < 4; ++ni) acc[mi][ni] = __builtin_amdgcn_mfma_f32_16x16x32_bf16(bfr[ni], af[mi], acc[mi][ni], 0, 0, 0);
;             __builtin_amdgcn_s_setprio(0);
;             __builtin_amdgcn_sched_barrier(0);
;         }
;         } else {
; #pragma unroll
;         for (int ks = 0; ks < 2; ++ks) {
;             bf16x8 bfr[4];
;             const int co = ((ks * 4 + kq) ^ swz) * 16;
; #pragma unroll
;             for (int ni = 0; ni < 4; ++ni) bfr[ni] = *(const bf16x8*)(sb + boff + ni * 2048 + co);
; #pragma unroll
;             for (int mh = 0; mh < 2; ++mh) {
;                 bf16x8 af[4];
; #pragma unroll
;                 for (int mi = 0; mi < 4; ++mi) af[mi] = *(const bf16x8*)(sb + aoff + (mh * 4 + mi) * 2048 + co);
;                 if (more) G_ISSUE1(kt + 1, st ^ 1, ks * 2 + mh);
;                 __builtin_amdgcn_sched_barrier(0);
;                 __builtin_amdgcn_s_setprio(1);
; #pragma unroll
;                 for (int mi = 0; mi < 4; ++mi)
; #pragma unroll
;                     for (int ni = 0; ni < 4; ++ni) acc[mh * 4 + mi][ni] = __builtin_amdgcn_mfma_f32_16x16x32_bf16(bfr[ni], af[mi], acc[mh * 4 + mi][ni], 0, 0, 0);
;                 __builtin_amdgcn_s_setprio(0);
;                 __builtin_amdgcn_sched_barrier(0);
;             }
;         }
.Lg1_dtskip2:
	s_waitcnt lgkmcnt(0)
	s_add_i32 s12, s12, 0x10000
	s_waitcnt vmcnt(0)
	s_add_u32 s38, s38, 0x80
	s_addc_u32 s39, s39, 0
	s_cmpk_lg_i32 s38, 0x780
	s_waitcnt vmcnt(0)
	s_barrier
	s_cbranch_scc1 .LBB0_255
	s_add_i32 s9, 0, 0x10000
	v_add_u32_e32 v80, s9, v149
	v_add_u32_e32 v149, v80, v148
	ds_read_b128 v[130:133], v149 offset:14336
	ds_read_b128 v[134:137], v149 offset:12288
	ds_read_b128 v[138:141], v149 offset:10240
	ds_read_b128 v[142:145], v149 offset:8192
	ds_read_b128 v[150:153], v149 offset:6144
	ds_read_b128 v[154:157], v149 offset:4096
	ds_read_b128 v[158:161], v149 offset:2048
	ds_read_b128 v[162:165], v149
	v_add_u32_e32 v147, s9, v147
	v_add_u32_e32 v148, v147, v148
	ds_read_b128 v[166:169], v148 offset:38912
	ds_read_b128 v[170:173], v148 offset:36864
	ds_read_b128 v[174:177], v148 offset:34816
	ds_read_b128 v[180:183], v148 offset:32768
	s_cmp_lg_u32 s101, 0
	s_cbranch_scc1 .Lg1_dtskip3
	s_setprio 1
	s_waitcnt lgkmcnt(0)
	v_mfma_f32_16x16x32_bf16 v[126:129], v[180:183], v[162:165], v[126:129]
	v_mfma_f32_16x16x32_bf16 v[122:125], v[174:177], v[162:165], v[122:125]
	v_mfma_f32_16x16x32_bf16 v[118:121], v[170:173], v[162:165], v[118:121]
	v_mfma_f32_16x16x32_bf16 v[114:117], v[166:169], v[162:165], v[114:117]
	v_mfma_f32_16x16x32_bf16 v[110:113], v[180:183], v[158:161], v[110:113]
	v_mfma_f32_16x16x32_bf16 v[106:109], v[174:177], v[158:161], v[106:109]
	v_mfma_f32_16x16x32_bf16 v[102:105], v[170:173], v[158:161], v[102:105]
	v_mfma_f32_16x16x32_bf16 v[98:101], v[166:169], v[158:161], v[98:101]
	v_mfma_f32_16x16x32_bf16 v[94:97], v[180:183], v[154:157], v[94:97]
	v_mfma_f32_16x16x32_bf16 v[90:93], v[174:177], v[154:157], v[90:93]
	v_mfma_f32_16x16x32_bf16 v[86:89], v[170:173], v[154:157], v[86:89]
	v_mfma_f32_16x16x32_bf16 v[82:85], v[166:169], v[154:157], v[82:85]
	v_mfma_f32_16x16x32_bf16 v[76:79], v[180:183], v[150:153], v[76:79]
	v_mfma_f32_16x16x32_bf16 v[72:75], v[174:177], v[150:153], v[72:75]
	v_mfma_f32_16x16x32_bf16 v[68:71], v[170:173], v[150:153], v[68:71]
	v_mfma_f32_16x16x32_bf16 v[64:67], v[166:169], v[150:153], v[64:67]
	v_mfma_f32_16x16x32_bf16 v[60:63], v[180:183], v[142:145], v[60:63]
	v_mfma_f32_16x16x32_bf16 v[56:59], v[174:177], v[142:145], v[56:59]
	v_mfma_f32_16x16x32_bf16 v[52:55], v[170:173], v[142:145], v[52:55]
	v_mfma_f32_16x16x32_bf16 v[48:51], v[166:169], v[142:145], v[48:51]
	v_mfma_f32_16x16x32_bf16 v[44:47], v[180:183], v[138:141], v[44:47]
	v_mfma_f32_16x16x32_bf16 v[40:43], v[174:177], v[138:141], v[40:43]
	v_mfma_f32_16x16x32_bf16 v[36:39], v[170:173], v[138:141], v[36:39]
	v_mfma_f32_16x16x32_bf16 v[32:35], v[166:169], v[138:141], v[32:35]
	v_mfma_f32_16x16x32_bf16 v[28:31], v[180:183], v[134:137], v[28:31]
	v_mfma_f32_16x16x32_bf16 v[24:27], v[174:177], v[134:137], v[24:27]
	v_mfma_f32_16x16x32_bf16 v[20:23], v[170:173], v[134:137], v[20:23]
	v_mfma_f32_16x16x32_bf16 v[16:19], v[166:169], v[134:137], v[16:19]
	v_mfma_f32_16x16x32_bf16 v[12:15], v[180:183], v[130:133], v[12:15]
	v_mfma_f32_16x16x32_bf16 v[8:11], v[174:177], v[130:133], v[8:11]
	v_mfma_f32_16x16x32_bf16 v[4:7], v[170:173], v[130:133], v[4:7]
	v_mfma_f32_16x16x32_bf16 v[0:3], v[166:169], v[130:133], v[0:3]
	s_setprio 0
.Lg1_dtskip3:
	s_waitcnt lgkmcnt(0)
	v_add_u32_e32 v80, v80, v146
	ds_read_b128 v[130:133], v80 offset:14336
	ds_read_b128 v[134:137], v80 offset:12288
	ds_read_b128 v[138:141], v80 offset:10240
	ds_read_b128 v[142:145], v80 offset:8192
	ds_read_b128 v[148:151], v80 offset:6144
	ds_read_b128 v[152:155], v80 offset:4096
	ds_read_b128 v[156:159], v80 offset:2048
	ds_read_b128 v[160:163], v80
	v_add_u32_e32 v80, v147, v146
	ds_read_b128 v[164:167], v80 offset:38912
	ds_read_b128 v[168:171], v80 offset:36864
	ds_read_b128 v[172:175], v80 offset:34816
	ds_read_b128 v[180:183], v80 offset:32768
	s_cmp_lg_u32 s101, 0
	s_cbranch_scc1 .Lg1_dtskip4
	s_setprio 1
	s_waitcnt lgkmcnt(0)
	v_mfma_f32_16x16x32_bf16 v[126:129], v[180:183], v[160:163], v[126:129]
	v_mfma_f32_16x16x32_bf16 v[122:125], v[172:175], v[160:163], v[122:125]
	v_mfma_f32_16x16x32_bf16 v[118:121], v[168:171], v[160:163], v[118:121]
	v_mfma_f32_16x16x32_bf16 v[114:117], v[164:167], v[160:163], v[114:117]
	v_mfma_f32_16x16x32_bf16 v[110:113], v[180:183], v[156:159], v[110:113]
	v_mfma_f32_16x16x32_bf16 v[106:109], v[172:175], v[156:159], v[106:109]
	v_mfma_f32_16x16x32_bf16 v[102:105], v[168:171], v[156:159], v[102:105]
	v_mfma_f32_16x16x32_bf16 v[98:101], v[164:167], v[156:159], v[98:101]
	v_mfma_f32_16x16x32_bf16 v[94:97], v[180:183], v[152:155], v[94:97]
	v_mfma_f32_16x16x32_bf16 v[90:93], v[172:175], v[152:155], v[90:93]
	v_mfma_f32_16x16x32_bf16 v[86:89], v[168:171], v[152:155], v[86:89]
	v_mfma_f32_16x16x32_bf16 v[82:85], v[164:167], v[152:155], v[82:85]
	v_mfma_f32_16x16x32_bf16 v[76:79], v[180:183], v[148:151], v[76:79]
	v_mfma_f32_16x16x32_bf16 v[72:75], v[172:175], v[148:151], v[72:75]
	v_mfma_f32_16x16x32_bf16 v[68:71], v[168:171], v[148:151], v[68:71]
	v_mfma_f32_16x16x32_bf16 v[64:67], v[164:167], v[148:151], v[64:67]
	v_mfma_f32_16x16x32_bf16 v[60:63], v[180:183], v[142:145], v[60:63]
	v_mfma_f32_16x16x32_bf16 v[56:59], v[172:175], v[142:145], v[56:59]
	v_mfma_f32_16x16x32_bf16 v[52:55], v[168:171], v[142:145], v[52:55]
	v_mfma_f32_16x16x32_bf16 v[48:51], v[164:167], v[142:145], v[48:51]
	v_mfma_f32_16x16x32_bf16 v[44:47], v[180:183], v[138:141], v[44:47]
	v_mfma_f32_16x16x32_bf16 v[40:43], v[172:175], v[138:141], v[40:43]
	v_mfma_f32_16x16x32_bf16 v[36:39], v[168:171], v[138:141], v[36:39]
	v_mfma_f32_16x16x32_bf16 v[32:35], v[164:167], v[138:141], v[32:35]
	v_mfma_f32_16x16x32_bf16 v[28:31], v[180:183], v[134:137], v[28:31]
	v_mfma_f32_16x16x32_bf16 v[24:27], v[172:175], v[134:137], v[24:27]
	v_mfma_f32_16x16x32_bf16 v[20:23], v[168:171], v[134:137], v[20:23]
	v_mfma_f32_16x16x32_bf16 v[16:19], v[164:167], v[134:137], v[16:19]
	v_mfma_f32_16x16x32_bf16 v[12:15], v[180:183], v[130:133], v[12:15]
	v_mfma_f32_16x16x32_bf16 v[8:11], v[172:175], v[130:133], v[8:11]
	v_mfma_f32_16x16x32_bf16 v[4:7], v[168:171], v[130:133], v[4:7]
	v_mfma_f32_16x16x32_bf16 v[0:3], v[164:167], v[130:133], v[0:3]
	s_setprio 0
.Lg1_dtskip4:
	s_waitcnt lgkmcnt(0)
	v_mov_b32_e32 v181, v210
	s_waitcnt vmcnt(0)
	s_barrier
	s_nop 0
	v_readfirstlane_b32 s9, v181
	s_ashr_i32 s57, s9, 8
	s_and_b32 s55, s9, 0xc0
	s_lshl_b32 s9, s9, 8
	s_and_b32 s9, s9, 0xffffc000
	v_bfe_u32 v156, v181, 4, 2
	s_or_b32 s54, s55, s36
	s_add_i32 s61, s9, 0
	v_and_b32_e32 v230, 63, v181
	v_and_b32_e32 v231, 15, v181
	v_lshlrev_b32_e32 v157, 2, v156
	s_cmpk_gt_i32 s54, 0x27f
	s_mov_b64 s[36:37], -1
	s_cbranch_scc1 .LBB0_259
	s_andn2_b64 vcc, exec, s[36:37]
	v_and_b32_e32 v179, 7, v181
	s_cbranch_vccz .LBB0_521

; template <int PASS>
; __device__ void ssd_item(const Params& p, int item, int l, unsigned char* smem) {
;     ...
;     unsigned soff[5];
; #pragma unroll
;     for (int i = 0; i < 5; ++i) { const int u = tid + 256 * i, lrow = u / 40, ci = u % 40;
;         const int scol = ci < 8 ? h * 64 + ci * 8 : (ci < 24 ? 512 + grp * 128 + (ci * 8 - 64) : 768 + grp * 128 + (ci * 8 - 192));
;         soff[i] = (unsigned)((lrow * 1024 + scol) * 2); }
;     for (int si = 0; si < NSUB; ++si) {
;         const int scn = dir ? (NSUB - 1 - si) : si;
;         const int t0 = seg * SEGLEN + scn * TSUB;
;         __syncthreads();
;         u32x4 raw[5];
; #pragma unroll
;         for (int i = 0; i < 5; ++i) raw[i] = *(const u32x4*)(xb_ + ((unsigned)(t0 * 2048) + soff[i]));
;     ...
;                 const int ii = 16 * it + idx; const float ci_ = s_c[ii];
;                 f32x4 gv;
; #pragma unroll
;                 for (int rg = 0; rg < 4; ++rg) {
;                     const int jj = 16 * jt + 4 * kq + rg;
;                     const bool ok = dir ? (jj >= ii) : (jj <= ii);
;                     const float e = __expf(ci_ - s_c[jj]) * s_dt[jj];
;                     gv[rg] = ok ? cb[rg] * e : 0.f;
;                 }
.LBB0_910:
	s_andn2_saveexec_b64 s[50:51], s[50:51]
	v_add_u32_e32 v47, s21, v45
	s_or_b64 exec, exec, s[50:51]
	v_lshlrev_b32_e32 v49, 11, v65
	s_lshl_b64 s[22:23], s[48:49], 24
	v_lshl_add_u32 v67, v46, 1, v49
	v_lshlrev_b32_e32 v46, 11, v64
	s_and_b64 s[24:25], exec, s[36:37]
	s_mov_b32 s20, 0x15800000
	v_lshl_add_u32 v68, v43, 1, v46
	v_lshlrev_b32_e32 v43, 11, v63
	s_cselect_b32 s24, s20, 0x16800000
	v_lshl_add_u32 v69, v41, 1, v43
	v_lshlrev_b32_e32 v41, 11, v62
	s_add_u32 s24, s92, s24
	v_lshl_add_u32 v70, v39, 1, v41
	s_addc_u32 s25, s93, 0
	v_lshlrev_b32_e32 v39, 11, v66
	v_lshlrev_b32_e32 v43, 4, v35
	v_lshlrev_b32_e32 v48, 2, v35
	v_lshl_add_u32 v71, v47, 1, v39
	s_add_u32 s96, s17, s22
	v_and_b32_e32 v39, 16, v34
	v_add_u32_e32 v56, v52, v43
	v_and_or_b32 v73, v33, -16, v53
	s_addc_u32 s97, s18, s23
	v_mad_u64_u32 v[58:59], s[22:23], v73, s0, v[56:57]
	v_mad_u64_u32 v[46:47], s[22:23], v73, s1, v[52:53]
	v_lshlrev_b32_e32 v33, 1, v39
	v_lshlrev_b32_e32 v80, 1, v48
	v_lshlrev_b32_e32 v32, 2, v32
	s_lshl_b32 s21, s21, 1
	v_add3_u32 v74, v46, v33, v80
	v_lshrrev_b32_e32 v33, 2, v53
	v_and_b32_e32 v46, 12, v32
	s_add_u32 s22, s24, s21
	v_or_b32_e32 v41, v39, v53
	v_or_b32_e32 v59, v39, v48
	v_lshl_or_b32 v39, v35, 3, v33
	v_or_b32_e32 v32, v34, v46
	s_addc_u32 s23, s25, 0
	v_ashrrev_i32_e32 v35, 31, v34
	v_lshlrev_b32_e32 v47, 1, v32
	v_lshl_add_u64 v[32:33], v[34:35], 1, s[22:23]
	v_lshl_add_u64 v[60:61], v[32:33], 0, v[80:81]
	v_lshlrev_b32_e32 v32, 1, v34
	v_mul_lo_u32 v34, v62, s0
	v_lshlrev_b32_e32 v35, 4, v37
	v_add3_u32 v77, v52, v34, v35
	v_lshlrev_b32_e32 v34, 7, v62
	v_sub_u32_e32 v79, v77, v34
	v_mul_lo_u32 v34, v63, s0
	v_lshlrev_b32_e32 v35, 4, v38
	v_add3_u32 v76, v52, v32, v80
	v_add3_u32 v80, v52, v34, v35
	v_lshlrev_b32_e32 v34, 7, v63
	v_sub_u32_e32 v83, v80, v34
	v_mul_lo_u32 v34, v64, s0
	v_lshlrev_b32_e32 v35, 4, v40
	v_add3_u32 v84, v52, v34, v35
	v_lshlrev_b32_e32 v34, 7, v64
	v_sub_u32_e32 v86, v84, v34
	v_mul_lo_u32 v34, v65, s0
	v_lshlrev_b32_e32 v35, 4, v42
	v_add3_u32 v87, v52, v34, v35
	v_lshlrev_b32_e32 v34, 7, v65
	v_sub_u32_e32 v89, v87, v34
	v_mul_lo_u32 v34, v66, s0
	v_lshlrev_b32_e32 v35, 1, v45
	v_add3_u32 v90, v52, v34, v35
	v_lshlrev_b32_e32 v34, 7, v66
	v_cmp_le_i32_e32 vcc, v59, v73
	v_sub_u32_e32 v92, v90, v34
	v_mad_u32_u24 v72, v41, s0, v56
	v_cndmask_b32_e64 v34, 0, 1, vcc
	v_cmp_ge_i32_e32 vcc, v59, v73
	v_mad_u32_u24 v41, v39, s3, v52
	v_mad_u32_u24 v32, v39, s0, v52
	v_cndmask_b32_e64 v35, 0, 1, vcc
	v_cndmask_b32_e64 v34, v35, v34, s[36:37]
	v_and_b32_e32 v34, 1, v34
	v_cmp_eq_u32_e64 s[58:59], 1, v34
	v_or_b32_e32 v34, 1, v59
	v_cmp_lt_i32_e32 vcc, v59, v73
	v_lshlrev_b32_e32 v33, 1, v46
	s_mov_b32 s20, 0
	v_cndmask_b32_e64 v35, 0, 1, vcc
	v_cmp_ge_i32_e32 vcc, v34, v73
	v_add_u32_e32 v75, v36, v43
	v_cmp_lt_u32_e64 s[48:49], 23, v37
	v_cndmask_b32_e64 v34, 0, 1, vcc
	v_cndmask_b32_e64 v34, v34, v35, s[36:37]
	v_and_b32_e32 v34, 1, v34
	v_cmp_eq_u32_e64 s[60:61], 1, v34
	v_or_b32_e32 v34, 2, v59
	v_cmp_le_i32_e32 vcc, v34, v73
	v_add_u32_e32 v78, 0xffffff80, v77
	v_cmp_lt_u32_e64 s[50:51], 23, v38
	v_cndmask_b32_e64 v35, 0, 1, vcc
	v_cmp_ge_i32_e32 vcc, v34, v73
	v_add_u32_e32 v82, 0xffffff80, v80
	v_cmp_lt_u32_e64 s[52:53], 23, v40
	v_cndmask_b32_e64 v34, 0, 1, vcc
	v_cndmask_b32_e64 v34, v34, v35, s[36:37]
	v_and_b32_e32 v34, 1, v34
	v_cmp_eq_u32_e64 s[62:63], 1, v34
	v_or_b32_e32 v34, 3, v59
	v_cmp_le_i32_e32 vcc, v34, v73
	v_add_u32_e32 v85, 0xffffff80, v84
	v_cmp_lt_u32_e64 s[54:55], 23, v42
	v_cndmask_b32_e64 v35, 0, 1, vcc
	v_cmp_ge_i32_e32 vcc, v34, v73
	v_add_u32_e32 v88, 0xffffff80, v87
	v_cmp_lt_u32_e64 s[56:57], 23, v44
	v_cndmask_b32_e64 v34, 0, 1, vcc
	v_cndmask_b32_e64 v34, v34, v35, s[36:37]
	v_and_b32_e32 v34, 1, v34
	v_add_u32_e32 v91, 0xffffff80, v90
	v_cmp_eq_u32_e64 s[64:65], 1, v34
	v_mov_b32_e32 v55, v54
	v_add_u32_e32 v93, v32, v33
	v_add_u32_e32 v94, v41, v47
	s_and_b64 s[22:23], exec, s[36:37]
	s_cselect_b32 s99, 0, 15
	s_cselect_b32 s100, 1, 14
	s_lshl_b32 s99, s99, 5
	s_add_i32 s99, s99, s12
	s_lshl_b32 s99, s99, 11
	s_lshl_b32 s100, s100, 5
	s_add_i32 s100, s100, s12
	s_lshl_b32 s100, s100, 11
	v_add_u32_e32 v140, s99, v70
	global_load_dwordx4 v[120:123], v140, s[96:97]
	v_add_u32_e32 v141, s99, v69
	global_load_dwordx4 v[124:127], v141, s[96:97]
	v_add_u32_e32 v140, s99, v68
	global_load_dwordx4 v[128:131], v140, s[96:97]
	v_add_u32_e32 v141, s99, v67
	global_load_dwordx4 v[132:135], v141, s[96:97]
	v_add_u32_e32 v140, s99, v71
	global_load_dwordx4 v[136:139], v140, s[96:97]
	v_add_u32_e32 v140, s100, v70
	global_load_dwordx4 v[142:145], v140, s[96:97]
	v_add_u32_e32 v141, s100, v69
	global_load_dwordx4 v[146:149], v141, s[96:97]
	v_add_u32_e32 v140, s100, v68
	global_load_dwordx4 v[150:153], v140, s[96:97]
	v_add_u32_e32 v141, s100, v67
	global_load_dwordx4 v[154:157], v141, s[96:97]
	v_add_u32_e32 v140, s100, v71
	global_load_dwordx4 v[158:161], v140, s[96:97]
	s_branch .LBB0_914

; template <int PASS>
; __device__ void ssd_item(const Params& p, int item, int l, unsigned char* smem) {
;     ...
;     for (int si = 0; si < NSUB; ++si) {
;         const int scn = dir ? (NSUB - 1 - si) : si;
;         const int t0 = seg * SEGLEN + scn * TSUB;
;         __syncthreads();
;         u32x4 raw[5];
; #pragma unroll
;         for (int i = 0; i < 5; ++i) raw[i] = *(const u32x4*)(xb_ + ((unsigned)(t0 * 2048) + soff[i]));
.LBB0_914:
	s_sub_i32 s21, 15, s20
	s_add_i32 s99, s20, 2
	s_sub_i32 s100, 13, s20
	s_and_b64 s[22:23], exec, s[36:37]
	s_cselect_b32 s101, s99, s100
	s_cselect_b32 s22, s20, s21
	s_lshl_b32 s21, s22, 5
	s_add_i32 s21, s21, s12
	s_lshl_b32 s101, s101, 5
	s_add_i32 s101, s101, s12
	s_lshl_b32 s101, s101, 11
	s_waitcnt lgkmcnt(0)
	s_barrier
	s_cmp_gt_u32 s20, 13
	s_cbranch_scc1 .Lssd3_tailwait
	s_waitcnt vmcnt(5)
	s_branch .Lssd3_w

; template <int PASS>
; __device__ void ssd_item(const Params& p, int item, int l, unsigned char* smem) {
;     ...
;         u32x4 raw[5];
; #pragma unroll
;         for (int i = 0; i < 5; ++i) raw[i] = *(const u32x4*)(xb_ + ((unsigned)(t0 * 2048) + soff[i]));
;         const float* s_dt = s_dta + scn * TSUB; const float* s_c = s_cA + scn * TSUB; const float* s_rs = s_rsA + scn * TSUB; const float* s_wl = s_wlA + scn * TSUB;
;         const float stot = s_totA[scn];
;         segtot += stot;
.Lssd3_w:
	s_bitcmp1_b32 s20, 0
	s_cbranch_scc1 .Lssd3_odd
	v_mov_b32_e32 v48, v120
	v_mov_b32_e32 v49, v121
	v_mov_b32_e32 v50, v122
	v_mov_b32_e32 v51, v123
	v_mov_b32_e32 v44, v124
	v_mov_b32_e32 v45, v125
	v_mov_b32_e32 v46, v126
	v_mov_b32_e32 v47, v127
	v_mov_b32_e32 v40, v128
	v_mov_b32_e32 v41, v129
	v_mov_b32_e32 v42, v130
	v_mov_b32_e32 v43, v131
	v_mov_b32_e32 v36, v132
	v_mov_b32_e32 v37, v133
	v_mov_b32_e32 v38, v134
	v_mov_b32_e32 v39, v135
	v_mov_b32_e32 v32, v136
	v_mov_b32_e32 v33, v137
	v_mov_b32_e32 v34, v138
	v_mov_b32_e32 v35, v139
	s_cmp_gt_u32 s20, 13
	s_cbranch_scc1 .Lssd3_join
	v_add_u32_e32 v140, s101, v70
	global_load_dwordx4 v[120:123], v140, s[96:97]
	v_add_u32_e32 v141, s101, v69
	global_load_dwordx4 v[124:127], v141, s[96:97]
	v_add_u32_e32 v140, s101, v68
	global_load_dwordx4 v[128:131], v140, s[96:97]
	v_add_u32_e32 v141, s101, v67
	global_load_dwordx4 v[132:135], v141, s[96:97]
	v_add_u32_e32 v140, s101, v71
	global_load_dwordx4 v[136:139], v140, s[96:97]
	s_branch .Lssd3_join
.Lssd3_odd:
	v_mov_b32_e32 v48, v142
	v_mov_b32_e32 v49, v143
	v_mov_b32_e32 v50, v144
	v_mov_b32_e32 v51, v145
	v_mov_b32_e32 v44, v146
	v_mov_b32_e32 v45, v147
	v_mov_b32_e32 v46, v148
	v_mov_b32_e32 v47, v149
	v_mov_b32_e32 v40, v150
	v_mov_b32_e32 v41, v151
	v_mov_b32_e32 v42, v152
	v_mov_b32_e32 v43, v153
	v_mov_b32_e32 v36, v154
	v_mov_b32_e32 v37, v155
	v_mov_b32_e32 v38, v156
	v_mov_b32_e32 v39, v157
	v_mov_b32_e32 v32, v158
	v_mov_b32_e32 v33, v159
	v_mov_b32_e32 v34, v160
	v_mov_b32_e32 v35, v161
	s_cmp_gt_u32 s20, 13
	s_cbranch_scc1 .Lssd3_join
	v_add_u32_e32 v140, s101, v70
	global_load_dwordx4 v[142:145], v140, s[96:97]
	v_add_u32_e32 v141, s101, v69
	global_load_dwordx4 v[146:149], v141, s[96:97]
	v_add_u32_e32 v140, s101, v68
	global_load_dwordx4 v[150:153], v140, s[96:97]
	v_add_u32_e32 v141, s101, v67
	global_load_dwordx4 v[154:157], v141, s[96:97]
	v_add_u32_e32 v140, s101, v71
	global_load_dwordx4 v[158:161], v140, s[96:97]
.Lssd3_join:
	v_lshl_add_u32 v96, s22, 7, v52
	s_mul_i32 s23, s22, 0xffffff84
	v_add_u32_e32 v97, s23, v96
	ds_read_b32 v95, v97 offset:54272
	s_and_saveexec_b64 s[24:25], s[38:39]
	s_xor_b64 s[66:67], exec, s[24:25]
	s_cbranch_execnz .LBB0_934
	s_andn2_saveexec_b64 s[66:67], s[66:67]
	s_cbranch_execnz .LBB0_939

; __device__ __forceinline__ unsigned pk2(float lo, float hi) { f32x2 v = {lo, hi}; bf16x2_t b = __builtin_convertvector(v, bf16x2_t); return __builtin_bit_cast(unsigned, b); }
; __device__ __forceinline__ float bflo(unsigned u) { return __uint_as_float(u << 16); }
; __device__ __forceinline__ float bfhi(unsigned u) { return __uint_as_float(u & 0xffff0000u); }
; template <int PASS>
; __device__ void ssd_item(const Params& p, int item, int l, unsigned char* smem) {
;     ...
;         for (int i = 0; i < 5; ++i) { const int u = tid + 256 * i, lrow = u / 40, ci = u % 40, lc = ci * 8; const u32x4 o = raw[i];
;             if (ci < 8) { *(u32x4*)(Xs + lrow * 72 + lc) = o; const float wl = s_wl[lrow];
;                 u32x4 o2; o2.x = pk2(bflo(o.x) * wl, bfhi(o.x) * wl); o2.y = pk2(bflo(o.y) * wl, bfhi(o.y) * wl); o2.z = pk2(bflo(o.z) * wl, bfhi(o.z) * wl); o2.w = pk2(bflo(o.w) * wl, bfhi(o.w) * wl);
;                 *(u32x4*)(Xws + lrow * 72 + lc) = o2; }
;             else if (ci < 24) *(u32x4*)(Bs + lrow * 136 + (lc - 64)) = o;
;             else *(u32x4*)(Cs + lrow * 136 + (lc - 192)) = o; }
;         __syncthreads();
;         if (PASS == 3) {
;             const int it = w >> 1, jt = w & 1;
;             f32x4 cb = (f32x4){0.f, 0.f, 0.f, 0.f};
;             {
;                 bf16x8 fb[4], fc[4];
; #pragma unroll
;                 for (int ks = 0; ks < 4; ++ks) { fb[ks] = *(const bf16x8*)(Bs + (16 * jt + idx) * 136 + ks * 32 + kq * 8); fc[ks] = *(const bf16x8*)(Cs + (16 * it + idx) * 136 + ks * 32 + kq * 8); }
;                 __builtin_amdgcn_sched_barrier(0);
; #pragma unroll
;                 for (int ks = 0; ks < 4; ++ks) cb = __builtin_amdgcn_mfma_f32_16x16x32_bf16(fb[ks], fc[ks], cb, 0, 0, 0);
;                 __builtin_amdgcn_sched_barrier(0);
;             }
;             {
;                 const int ii = 16 * it + idx; const float ci_ = s_c[ii];
;                 f32x4 gv;
; #pragma unroll
;                 for (int rg = 0; rg < 4; ++rg) {
;                     const int jj = 16 * jt + 4 * kq + rg;
;                     const bool ok = dir ? (jj >= ii) : (jj <= ii);
;                     const float e = __expf(ci_ - s_c[jj]) * s_dt[jj];
;                     gv[rg] = ok ? cb[rg] * e : 0.f;
;                 }
;                 st4bf(Gs + ii * 40 + 16 * jt + 4 * kq, gv);
.LBB0_924:
	ds_write_b128 v92, v[32:35] offset:17408
	v_lshl_add_u32 v36, v66, 2, v96
	ds_read_b32 v36, v36 offset:50688
	v_lshlrev_b32_e32 v38, 16, v32
	v_and_b32_e32 v39, 0xffff0000, v32
	s_waitcnt lgkmcnt(0)
	v_pk_mul_f32 v[38:39], v[36:37], v[38:39] op_sel_hi:[0,1]
	v_cvt_pk_bf16_f32 v32, v38, v39
	v_lshlrev_b32_e32 v38, 16, v33
	v_and_b32_e32 v39, 0xffff0000, v33
	v_pk_mul_f32 v[38:39], v[36:37], v[38:39] op_sel_hi:[0,1]
	v_cvt_pk_bf16_f32 v33, v38, v39
	v_lshlrev_b32_e32 v38, 16, v34
	v_and_b32_e32 v39, 0xffff0000, v34
	v_pk_mul_f32 v[38:39], v[36:37], v[38:39] op_sel_hi:[0,1]
	v_cvt_pk_bf16_f32 v34, v38, v39
	v_lshlrev_b32_e32 v38, 16, v35
	v_and_b32_e32 v39, 0xffff0000, v35
	v_pk_mul_f32 v[36:37], v[36:37], v[38:39] op_sel_hi:[0,1]
	v_cvt_pk_bf16_f32 v35, v36, v37
	ds_write_b128 v92, v[32:35] offset:22016
.LBB0_925:
	s_or_b64 exec, exec, s[66:67]
	s_waitcnt lgkmcnt(0)
	s_barrier
	ds_read_b128 v[32:35], v72
	ds_read_b128 v[36:39], v58 offset:8704
	ds_read_b128 v[42:45], v72 offset:64
	ds_read_b128 v[46:49], v58 offset:8768
	ds_read_b128 v[98:101], v72 offset:128
	ds_read_b128 v[102:105], v58 offset:8832
	ds_read_b128 v[106:109], v72 offset:192
	ds_read_b128 v[110:113], v58 offset:8896
	s_mulk_i32 s22, 0x7c
	v_add_u32_e32 v40, s22, v97
	s_waitcnt lgkmcnt(6)
	v_mfma_f32_16x16x32_bf16 v[32:35], v[32:35], v[36:39], 0
	s_waitcnt lgkmcnt(4)
	v_mfma_f32_16x16x32_bf16 v[32:35], v[42:45], v[46:49], v[32:35]
	s_waitcnt lgkmcnt(2)
	v_mfma_f32_16x16x32_bf16 v[32:35], v[98:101], v[102:105], v[32:35]
	s_waitcnt lgkmcnt(0)
	v_mfma_f32_16x16x32_bf16 v[32:35], v[106:109], v[110:113], v[32:35]
	v_lshl_add_u32 v36, v73, 2, v96
	ds_read_b32 v37, v36 offset:46592
	v_mov_b32_e32 v36, 0
	v_lshl_add_u32 v39, v59, 2, v40
	v_mov_b32_e32 v38, 0
	s_and_saveexec_b64 s[66:67], s[58:59]
	s_cbranch_execnz .LBB0_963
	s_or_b64 exec, exec, s[66:67]
	v_mov_b32_e32 v32, 0
	s_and_saveexec_b64 s[66:67], s[60:61]
	s_cbranch_execnz .LBB0_964

; __device__ __forceinline__ unsigned pk2(float lo, float hi) { f32x2 v = {lo, hi}; bf16x2_t b = __builtin_convertvector(v, bf16x2_t); return __builtin_bit_cast(unsigned, b); }
; __device__ __forceinline__ float bflo(unsigned u) { return __uint_as_float(u << 16); }
; __device__ __forceinline__ float bfhi(unsigned u) { return __uint_as_float(u & 0xffff0000u); }
; template <int PASS>
; __device__ void ssd_item(const Params& p, int item, int l, unsigned char* smem) {
;     ...
;         for (int i = 0; i < 5; ++i) { const int u = tid + 256 * i, lrow = u / 40, ci = u % 40, lc = ci * 8; const u32x4 o = raw[i];
;             if (ci < 8) { *(u32x4*)(Xs + lrow * 72 + lc) = o; const float wl = s_wl[lrow];
;                 u32x4 o2; o2.x = pk2(bflo(o.x) * wl, bfhi(o.x) * wl); o2.y = pk2(bflo(o.y) * wl, bfhi(o.y) * wl); o2.z = pk2(bflo(o.z) * wl, bfhi(o.z) * wl); o2.w = pk2(bflo(o.w) * wl, bfhi(o.w) * wl);
;                 *(u32x4*)(Xws + lrow * 72 + lc) = o2; }
;             else if (ci < 24) *(u32x4*)(Bs + lrow * 136 + (lc - 64)) = o;
;             else *(u32x4*)(Cs + lrow * 136 + (lc - 192)) = o; }
.LBB0_934:
	s_and_saveexec_b64 s[24:25], s[48:49]
	s_xor_b64 vcc, exec, s[24:25]
	s_cbranch_execz .LBB0_936
	ds_write_b128 v77, v[48:51] offset:8320
.LBB0_936:
	s_andn2_saveexec_b64 vcc, vcc
	s_cbranch_execz .LBB0_938
	ds_write_b128 v78, v[48:51]

; __device__ __forceinline__ unsigned pk2(float lo, float hi) { f32x2 v = {lo, hi}; bf16x2_t b = __builtin_convertvector(v, bf16x2_t); return __builtin_bit_cast(unsigned, b); }
; __device__ __forceinline__ float bflo(unsigned u) { return __uint_as_float(u << 16); }
; __device__ __forceinline__ float bfhi(unsigned u) { return __uint_as_float(u & 0xffff0000u); }
; template <int PASS>
; __device__ void ssd_item(const Params& p, int item, int l, unsigned char* smem) {
;     ...
;         for (int i = 0; i < 5; ++i) { const int u = tid + 256 * i, lrow = u / 40, ci = u % 40, lc = ci * 8; const u32x4 o = raw[i];
;             if (ci < 8) { *(u32x4*)(Xs + lrow * 72 + lc) = o; const float wl = s_wl[lrow];
;                 u32x4 o2; o2.x = pk2(bflo(o.x) * wl, bfhi(o.x) * wl); o2.y = pk2(bflo(o.y) * wl, bfhi(o.y) * wl); o2.z = pk2(bflo(o.z) * wl, bfhi(o.z) * wl); o2.w = pk2(bflo(o.w) * wl, bfhi(o.w) * wl);
;                 *(u32x4*)(Xws + lrow * 72 + lc) = o2; }
;             else if (ci < 24) *(u32x4*)(Bs + lrow * 136 + (lc - 64)) = o;
;             else *(u32x4*)(Cs + lrow * 136 + (lc - 192)) = o; }
.LBB0_939:
	ds_write_b128 v79, v[48:51] offset:17408
	v_lshl_add_u32 v98, v62, 2, v96
	ds_read_b32 v98, v98 offset:50688
	v_lshlrev_b32_e32 v100, 16, v48
	v_and_b32_e32 v101, 0xffff0000, v48
	s_waitcnt lgkmcnt(0)
	v_pk_mul_f32 v[100:101], v[98:99], v[100:101] op_sel_hi:[0,1]
	v_cvt_pk_bf16_f32 v48, v100, v101
	v_lshlrev_b32_e32 v100, 16, v49
	v_and_b32_e32 v101, 0xffff0000, v49
	v_pk_mul_f32 v[100:101], v[98:99], v[100:101] op_sel_hi:[0,1]
	v_cvt_pk_bf16_f32 v49, v100, v101
	v_lshlrev_b32_e32 v100, 16, v50
	v_and_b32_e32 v101, 0xffff0000, v50
	v_pk_mul_f32 v[100:101], v[98:99], v[100:101] op_sel_hi:[0,1]
	v_cvt_pk_bf16_f32 v50, v100, v101
	v_lshlrev_b32_e32 v100, 16, v51
	v_and_b32_e32 v101, 0xffff0000, v51
	v_pk_mul_f32 v[98:99], v[98:99], v[100:101] op_sel_hi:[0,1]
	v_cvt_pk_bf16_f32 v51, v98, v99
	ds_write_b128 v79, v[48:51] offset:22016
	s_or_b64 exec, exec, s[66:67]
	s_and_saveexec_b64 s[24:25], s[40:41]
	s_xor_b64 s[66:67], exec, s[24:25]
	s_cbranch_execz .LBB0_917
.LBB0_940:
	s_and_saveexec_b64 s[24:25], s[50:51]
	s_xor_b64 vcc, exec, s[24:25]
	s_cbranch_execz .LBB0_942
	ds_write_b128 v80, v[44:47] offset:8320
.LBB0_942:
	s_andn2_saveexec_b64 vcc, vcc
	s_cbranch_execz .LBB0_944
	ds_write_b128 v82, v[44:47]

; __device__ __forceinline__ unsigned pk2(float lo, float hi) { f32x2 v = {lo, hi}; bf16x2_t b = __builtin_convertvector(v, bf16x2_t); return __builtin_bit_cast(unsigned, b); }
; __device__ __forceinline__ float bflo(unsigned u) { return __uint_as_float(u << 16); }
; __device__ __forceinline__ float bfhi(unsigned u) { return __uint_as_float(u & 0xffff0000u); }
; template <int PASS>
; __device__ void ssd_item(const Params& p, int item, int l, unsigned char* smem) {
;     ...
;         for (int i = 0; i < 5; ++i) { const int u = tid + 256 * i, lrow = u / 40, ci = u % 40, lc = ci * 8; const u32x4 o = raw[i];
;             if (ci < 8) { *(u32x4*)(Xs + lrow * 72 + lc) = o; const float wl = s_wl[lrow];
;                 u32x4 o2; o2.x = pk2(bflo(o.x) * wl, bfhi(o.x) * wl); o2.y = pk2(bflo(o.y) * wl, bfhi(o.y) * wl); o2.z = pk2(bflo(o.z) * wl, bfhi(o.z) * wl); o2.w = pk2(bflo(o.w) * wl, bfhi(o.w) * wl);
;                 *(u32x4*)(Xws + lrow * 72 + lc) = o2; }
;             else if (ci < 24) *(u32x4*)(Bs + lrow * 136 + (lc - 64)) = o;
;             else *(u32x4*)(Cs + lrow * 136 + (lc - 192)) = o; }
.LBB0_945:
	ds_write_b128 v83, v[44:47] offset:17408
	v_lshl_add_u32 v48, v63, 2, v96
	ds_read_b32 v48, v48 offset:50688
	v_lshlrev_b32_e32 v50, 16, v44
	v_and_b32_e32 v51, 0xffff0000, v44
	s_waitcnt lgkmcnt(0)
	v_pk_mul_f32 v[50:51], v[48:49], v[50:51] op_sel_hi:[0,1]
	v_cvt_pk_bf16_f32 v44, v50, v51
	v_lshlrev_b32_e32 v50, 16, v45
	v_and_b32_e32 v51, 0xffff0000, v45
	v_pk_mul_f32 v[50:51], v[48:49], v[50:51] op_sel_hi:[0,1]
	v_cvt_pk_bf16_f32 v45, v50, v51
	v_lshlrev_b32_e32 v50, 16, v46
	v_and_b32_e32 v51, 0xffff0000, v46
	v_pk_mul_f32 v[50:51], v[48:49], v[50:51] op_sel_hi:[0,1]
	v_cvt_pk_bf16_f32 v46, v50, v51
	v_lshlrev_b32_e32 v50, 16, v47
	v_and_b32_e32 v51, 0xffff0000, v47
	v_pk_mul_f32 v[48:49], v[48:49], v[50:51] op_sel_hi:[0,1]
	v_cvt_pk_bf16_f32 v47, v48, v49
	ds_write_b128 v83, v[44:47] offset:22016
	s_or_b64 exec, exec, s[66:67]
	s_and_saveexec_b64 s[24:25], s[42:43]
	s_xor_b64 s[66:67], exec, s[24:25]
	s_cbranch_execz .LBB0_919
.LBB0_946:
	s_and_saveexec_b64 s[24:25], s[52:53]
	s_xor_b64 vcc, exec, s[24:25]
	s_cbranch_execz .LBB0_948
	ds_write_b128 v84, v[40:43] offset:8320
.LBB0_948:
	s_andn2_saveexec_b64 vcc, vcc
	s_cbranch_execz .LBB0_950
	ds_write_b128 v85, v[40:43]

; __device__ __forceinline__ unsigned pk2(float lo, float hi) { f32x2 v = {lo, hi}; bf16x2_t b = __builtin_convertvector(v, bf16x2_t); return __builtin_bit_cast(unsigned, b); }
; __device__ __forceinline__ float bflo(unsigned u) { return __uint_as_float(u << 16); }
; __device__ __forceinline__ float bfhi(unsigned u) { return __uint_as_float(u & 0xffff0000u); }
; template <int PASS>
; __device__ void ssd_item(const Params& p, int item, int l, unsigned char* smem) {
;     ...
;         for (int i = 0; i < 5; ++i) { const int u = tid + 256 * i, lrow = u / 40, ci = u % 40, lc = ci * 8; const u32x4 o = raw[i];
;             if (ci < 8) { *(u32x4*)(Xs + lrow * 72 + lc) = o; const float wl = s_wl[lrow];
;                 u32x4 o2; o2.x = pk2(bflo(o.x) * wl, bfhi(o.x) * wl); o2.y = pk2(bflo(o.y) * wl, bfhi(o.y) * wl); o2.z = pk2(bflo(o.z) * wl, bfhi(o.z) * wl); o2.w = pk2(bflo(o.w) * wl, bfhi(o.w) * wl);
;                 *(u32x4*)(Xws + lrow * 72 + lc) = o2; }
;             else if (ci < 24) *(u32x4*)(Bs + lrow * 136 + (lc - 64)) = o;
;             else *(u32x4*)(Cs + lrow * 136 + (lc - 192)) = o; }
.LBB0_951:
	ds_write_b128 v86, v[40:43] offset:17408
	v_lshl_add_u32 v44, v64, 2, v96
	ds_read_b32 v44, v44 offset:50688
	v_lshlrev_b32_e32 v46, 16, v40
	v_and_b32_e32 v47, 0xffff0000, v40
	s_waitcnt lgkmcnt(0)
	v_pk_mul_f32 v[46:47], v[44:45], v[46:47] op_sel_hi:[0,1]
	v_cvt_pk_bf16_f32 v40, v46, v47
	v_lshlrev_b32_e32 v46, 16, v41
	v_and_b32_e32 v47, 0xffff0000, v41
	v_pk_mul_f32 v[46:47], v[44:45], v[46:47] op_sel_hi:[0,1]
	v_cvt_pk_bf16_f32 v41, v46, v47
	v_lshlrev_b32_e32 v46, 16, v42
	v_and_b32_e32 v47, 0xffff0000, v42
	v_pk_mul_f32 v[46:47], v[44:45], v[46:47] op_sel_hi:[0,1]
	v_cvt_pk_bf16_f32 v42, v46, v47
	v_lshlrev_b32_e32 v46, 16, v43
	v_and_b32_e32 v47, 0xffff0000, v43
	v_pk_mul_f32 v[44:45], v[44:45], v[46:47] op_sel_hi:[0,1]
	v_cvt_pk_bf16_f32 v43, v44, v45
	ds_write_b128 v86, v[40:43] offset:22016
	s_or_b64 exec, exec, s[66:67]
	s_and_saveexec_b64 s[24:25], s[44:45]
	s_xor_b64 s[66:67], exec, s[24:25]
	s_cbranch_execz .LBB0_921
.LBB0_952:
	s_and_saveexec_b64 s[24:25], s[54:55]
	s_xor_b64 vcc, exec, s[24:25]
	s_cbranch_execz .LBB0_954
	ds_write_b128 v87, v[36:39] offset:8320
.LBB0_954:
	s_andn2_saveexec_b64 vcc, vcc
	s_cbranch_execz .LBB0_956
	ds_write_b128 v88, v[36:39]

; __device__ __forceinline__ unsigned pk2(float lo, float hi) { f32x2 v = {lo, hi}; bf16x2_t b = __builtin_convertvector(v, bf16x2_t); return __builtin_bit_cast(unsigned, b); }
; __device__ __forceinline__ float bflo(unsigned u) { return __uint_as_float(u << 16); }
; __device__ __forceinline__ float bfhi(unsigned u) { return __uint_as_float(u & 0xffff0000u); }
; template <int PASS>
; __device__ void ssd_item(const Params& p, int item, int l, unsigned char* smem) {
;     ...
;         for (int i = 0; i < 5; ++i) { const int u = tid + 256 * i, lrow = u / 40, ci = u % 40, lc = ci * 8; const u32x4 o = raw[i];
;             if (ci < 8) { *(u32x4*)(Xs + lrow * 72 + lc) = o; const float wl = s_wl[lrow];
;                 u32x4 o2; o2.x = pk2(bflo(o.x) * wl, bfhi(o.x) * wl); o2.y = pk2(bflo(o.y) * wl, bfhi(o.y) * wl); o2.z = pk2(bflo(o.z) * wl, bfhi(o.z) * wl); o2.w = pk2(bflo(o.w) * wl, bfhi(o.w) * wl);
;                 *(u32x4*)(Xws + lrow * 72 + lc) = o2; }
;             else if (ci < 24) *(u32x4*)(Bs + lrow * 136 + (lc - 64)) = o;
;             else *(u32x4*)(Cs + lrow * 136 + (lc - 192)) = o; }
.LBB0_957:
	ds_write_b128 v89, v[36:39] offset:17408
	v_lshl_add_u32 v40, v65, 2, v96
	ds_read_b32 v40, v40 offset:50688
	v_lshlrev_b32_e32 v42, 16, v36
	v_and_b32_e32 v43, 0xffff0000, v36
	s_waitcnt lgkmcnt(0)
	v_pk_mul_f32 v[42:43], v[40:41], v[42:43] op_sel_hi:[0,1]
	v_cvt_pk_bf16_f32 v36, v42, v43
	v_lshlrev_b32_e32 v42, 16, v37
	v_and_b32_e32 v43, 0xffff0000, v37
	v_pk_mul_f32 v[42:43], v[40:41], v[42:43] op_sel_hi:[0,1]
	v_cvt_pk_bf16_f32 v37, v42, v43
	v_lshlrev_b32_e32 v42, 16, v38
	v_and_b32_e32 v43, 0xffff0000, v38
	v_pk_mul_f32 v[42:43], v[40:41], v[42:43] op_sel_hi:[0,1]
	v_cvt_pk_bf16_f32 v38, v42, v43
	v_lshlrev_b32_e32 v42, 16, v39
	v_and_b32_e32 v43, 0xffff0000, v39
	v_pk_mul_f32 v[40:41], v[40:41], v[42:43] op_sel_hi:[0,1]
	v_cvt_pk_bf16_f32 v39, v40, v41
	ds_write_b128 v89, v[36:39] offset:22016
	s_or_b64 exec, exec, s[66:67]
	s_and_saveexec_b64 s[24:25], s[46:47]
	s_xor_b64 s[66:67], exec, s[24:25]
	s_cbranch_execz .LBB0_923
.LBB0_958:
	s_and_saveexec_b64 s[24:25], s[56:57]
	s_xor_b64 vcc, exec, s[24:25]
	s_cbranch_execz .LBB0_960
	ds_write_b128 v90, v[32:35] offset:8320
.LBB0_960:
	s_andn2_saveexec_b64 vcc, vcc
	s_cbranch_execz .LBB0_962
	ds_write_b128 v91, v[32:35]
